# speedup vs baseline: 1.0204x; 1.0025x over previous
; __device__ __forceinline__ float bf2f(u16 v) { return __uint_as_float(((uint32_t)v) << 16); }
; __device__ __forceinline__ uint2 pack4(float a, float b, float c, float d) { return make_uint2(pack2(a, b), pack2(c, d)); }
; __device__ __forceinline__ void store_pair16(u16* rowbase, const int fq, uint2 a, uint2 b) {
;   auto r0 = __builtin_amdgcn_permlane16_swap(a.x, b.x, false, false);
;   auto r1 = __builtin_amdgcn_permlane16_swap(a.y, b.y, false, false);
;   *(uint4*)(rowbase + (fq & 1) * 16 + (fq >> 1) * 8) = make_uint4(r0[0], r1[0], r0[1], r1[1]);
; }
; __device__ __forceinline__ void load_pair16(const u16* rowbase, const int fq, uint2& a, uint2& b) {
;   const uint4 v = *(const uint4*)(rowbase + (fq & 1) * 16 + (fq >> 1) * 8);
;   auto r0 = __builtin_amdgcn_permlane16_swap(v.x, v.z, false, false);
;   auto r1 = __builtin_amdgcn_permlane16_swap(v.y, v.w, false, false);
;   a = make_uint2(r0[0], r1[0]); b = make_uint2(r0[1], r1[1]);
; }
; __global__ void __launch_bounds__(NTHREADS, 2) fwd_megakernel(Params p_arg) {
;     ...
;       unsigned eoff = (unsigned)((brow + wr * 128 + fr) * 1024 + bcol + wc * 64);
;       asm volatile("" : "+v"(eoff));
; #pragma unroll
;       for (int m = 0; m < 8; ++m) {
; #pragma unroll
;         for (int np = 0; np < 2; ++np) {
;           uint2 rr[2], ov[2];
;           load_pair16(ZSBp + (eoff + (unsigned)(m * 16 * 1024 + np * 32)), fq, rr[0], rr[1]);
; #pragma unroll
;           for (int q = 0; q < 2; ++q) {
;             const int n = np * 2 + q;
;             ov[q] = pack4(acc[m][n][0] * bf2f((u16)(rr[q].x & 0xffffu)), acc[m][n][1] * bf2f((u16)(rr[q].x >> 16)),
;                           acc[m][n][2] * bf2f((u16)(rr[q].y & 0xffffu)), acc[m][n][3] * bf2f((u16)(rr[q].y >> 16)));
;           }
;           store_pair16(H + (eoff + (unsigned)(m * 16 * 1024 + np * 32)), fq, ov[0], ov[1]);
;         }
;         if (m == 3) __builtin_amdgcn_sched_barrier(0);
;       }
.LBB0_377:
	v_add_u32_e32 v0, s6, v156
	v_lshl_add_u32 v0, v0, 10, s8
	v_or_b32_e32 v0, s18, v0
	s_nop 0
	v_lshlrev_b64 v[26:27], 1, v[0:1]
	v_lshl_add_u64 v[14:15], v[132:133], 0, v[26:27]
	v_mov_b32_e32 v72, v0
	v_mov_b32_e32 v73, v1
	v_lshlrev_b64 v[72:73], 1, v[72:73]
	v_lshl_add_u64 v[72:73], v[132:133], 0, v[72:73]
	global_load_dwordx4 v[180:183], v[72:73], off
	v_add_u32_e32 v72, 0x20, v0
	v_mov_b32_e32 v73, v1
	v_lshlrev_b64 v[72:73], 1, v[72:73]
	v_lshl_add_u64 v[72:73], v[132:133], 0, v[72:73]
	global_load_dwordx4 v[184:187], v[72:73], off
	v_add_u32_e32 v72, 0x4000, v0
	v_mov_b32_e32 v73, v1
	v_lshlrev_b64 v[72:73], 1, v[72:73]
	v_lshl_add_u64 v[72:73], v[132:133], 0, v[72:73]
	global_load_dwordx4 v[188:191], v[72:73], off
	v_add_u32_e32 v72, 0x4020, v0
	v_mov_b32_e32 v73, v1
	v_lshlrev_b64 v[72:73], 1, v[72:73]
	v_lshl_add_u64 v[72:73], v[132:133], 0, v[72:73]
	global_load_dwordx4 v[196:199], v[72:73], off
	v_add_u32_e32 v72, 0x8000, v0
	v_mov_b32_e32 v73, v1
	v_lshlrev_b64 v[72:73], 1, v[72:73]
	v_lshl_add_u64 v[72:73], v[132:133], 0, v[72:73]
	global_load_dwordx4 v[200:203], v[72:73], off
	v_add_u32_e32 v72, 0x8020, v0
	v_mov_b32_e32 v73, v1
	v_lshlrev_b64 v[72:73], 1, v[72:73]
	v_lshl_add_u64 v[72:73], v[132:133], 0, v[72:73]
	global_load_dwordx4 v[204:207], v[72:73], off
	v_add_u32_e32 v72, 0xc000, v0
	v_mov_b32_e32 v73, v1
	v_lshlrev_b64 v[72:73], 1, v[72:73]
	v_lshl_add_u64 v[72:73], v[132:133], 0, v[72:73]
	global_load_dwordx4 v[208:211], v[72:73], off
	v_add_u32_e32 v72, 0xc020, v0
	v_mov_b32_e32 v73, v1
	v_lshlrev_b64 v[72:73], 1, v[72:73]
	v_lshl_add_u64 v[72:73], v[132:133], 0, v[72:73]
	global_load_dwordx4 v[212:215], v[72:73], off
	v_add_u32_e32 v72, 0x10000, v0
	v_mov_b32_e32 v73, v1
	v_lshlrev_b64 v[72:73], 1, v[72:73]
	v_lshl_add_u64 v[72:73], v[132:133], 0, v[72:73]
	global_load_dwordx4 v[216:219], v[72:73], off
	v_add_u32_e32 v72, 0x10020, v0
	v_mov_b32_e32 v73, v1
	v_lshlrev_b64 v[72:73], 1, v[72:73]
	v_lshl_add_u64 v[72:73], v[132:133], 0, v[72:73]
	global_load_dwordx4 v[220:223], v[72:73], off
	v_add_u32_e32 v72, 0x14000, v0
	v_mov_b32_e32 v73, v1
	v_lshlrev_b64 v[72:73], 1, v[72:73]
	v_lshl_add_u64 v[72:73], v[132:133], 0, v[72:73]
	global_load_dwordx4 v[228:231], v[72:73], off
	v_add_u32_e32 v72, 0x14020, v0
	v_mov_b32_e32 v73, v1
	v_lshlrev_b64 v[72:73], 1, v[72:73]
	v_lshl_add_u64 v[72:73], v[132:133], 0, v[72:73]
	global_load_dwordx4 v[232:235], v[72:73], off
	v_add_u32_e32 v72, 0x18000, v0
	v_mov_b32_e32 v73, v1
	v_lshlrev_b64 v[72:73], 1, v[72:73]
	v_lshl_add_u64 v[72:73], v[132:133], 0, v[72:73]
	global_load_dwordx4 v[236:239], v[72:73], off
	v_add_u32_e32 v72, 0x18020, v0
	v_mov_b32_e32 v73, v1
	v_lshlrev_b64 v[72:73], 1, v[72:73]
	v_lshl_add_u64 v[72:73], v[132:133], 0, v[72:73]
	global_load_dwordx4 v[240:243], v[72:73], off
	v_add_u32_e32 v72, 0x1c000, v0
	v_mov_b32_e32 v73, v1
	v_lshlrev_b64 v[72:73], 1, v[72:73]
	v_lshl_add_u64 v[72:73], v[132:133], 0, v[72:73]
	global_load_dwordx4 v[244:247], v[72:73], off
	v_add_u32_e32 v72, 0x1c020, v0
	v_mov_b32_e32 v73, v1
	v_lshlrev_b64 v[72:73], 1, v[72:73]
	v_lshl_add_u64 v[72:73], v[132:133], 0, v[72:73]
	global_load_dwordx4 v[248:251], v[72:73], off
	v_lshl_add_u64 v[26:27], v[134:135], 0, v[26:27]
	s_waitcnt vmcnt(15)
	v_mov_b32_e32 v14, v180
	v_mov_b32_e32 v15, v181
	v_mov_b32_e32 v16, v182
	v_mov_b32_e32 v17, v183
	v_mov_b32_e32 v70, v16
	v_mov_b32_e32 v71, v17
	s_nop 0
	v_permlane16_swap_b32_e32 v14, v70
	v_permlane16_swap_b32_e32 v15, v71
	v_lshlrev_b32_e32 v16, 16, v14
	v_and_b32_e32 v17, 0xffff0000, v14
	v_lshlrev_b32_e32 v14, 16, v15
	v_and_b32_e32 v15, 0xffff0000, v15
	v_pk_mul_f32 v[16:17], v[126:127], v[16:17]
	v_pk_mul_f32 v[28:29], v[128:129], v[14:15]
	v_cvt_pk_bf16_f32 v14, v16, v17
	v_cvt_pk_bf16_f32 v15, v28, v29
	v_lshlrev_b32_e32 v16, 16, v70
	v_and_b32_e32 v17, 0xffff0000, v70
	v_lshlrev_b32_e32 v28, 16, v71
	v_and_b32_e32 v29, 0xffff0000, v71
	v_pk_mul_f32 v[16:17], v[122:123], v[16:17]
	v_pk_mul_f32 v[28:29], v[124:125], v[28:29]
	v_cvt_pk_bf16_f32 v16, v16, v17
	v_cvt_pk_bf16_f32 v17, v28, v29
	s_nop 0
	v_permlane16_swap_b32_e32 v14, v16
	v_permlane16_swap_b32_e32 v15, v17
	global_store_dwordx4 v[26:27], v[14:17], off
	s_nop 1
	v_add_u32_e32 v14, 32, v0
	v_mov_b32_e32 v15, v1
	v_lshlrev_b64 v[26:27], 1, v[14:15]
	v_lshl_add_u64 v[14:15], v[132:133], 0, v[26:27]
	v_lshl_add_u64 v[26:27], v[134:135], 0, v[26:27]
	s_waitcnt vmcnt(15)
	v_mov_b32_e32 v14, v184
	v_mov_b32_e32 v15, v185
	v_mov_b32_e32 v16, v186
	v_mov_b32_e32 v17, v187
	v_mov_b32_e32 v70, v16
	v_mov_b32_e32 v71, v17
	s_nop 0
	v_permlane16_swap_b32_e32 v14, v70
	v_permlane16_swap_b32_e32 v15, v71
	v_lshlrev_b32_e32 v16, 16, v14
	v_and_b32_e32 v17, 0xffff0000, v14
	v_lshlrev_b32_e32 v14, 16, v15
	v_and_b32_e32 v15, 0xffff0000, v15
	v_pk_mul_f32 v[16:17], v[118:119], v[16:17]
	v_pk_mul_f32 v[28:29], v[120:121], v[14:15]
	v_cvt_pk_bf16_f32 v14, v16, v17
	v_cvt_pk_bf16_f32 v15, v28, v29
	v_lshlrev_b32_e32 v16, 16, v70
	v_and_b32_e32 v17, 0xffff0000, v70
	v_lshlrev_b32_e32 v28, 16, v71
	v_and_b32_e32 v29, 0xffff0000, v71
	v_pk_mul_f32 v[16:17], v[114:115], v[16:17]
	v_pk_mul_f32 v[28:29], v[116:117], v[28:29]
	v_cvt_pk_bf16_f32 v16, v16, v17
	v_cvt_pk_bf16_f32 v17, v28, v29
	s_nop 0
	v_permlane16_swap_b32_e32 v14, v16
	v_permlane16_swap_b32_e32 v15, v17
	global_store_dwordx4 v[26:27], v[14:17], off
	s_nop 1
	v_add_u32_e32 v14, 0x4000, v0
	v_mov_b32_e32 v15, v1
	v_lshlrev_b64 v[26:27], 1, v[14:15]
	v_lshl_add_u64 v[14:15], v[132:133], 0, v[26:27]
	v_lshl_add_u64 v[26:27], v[134:135], 0, v[26:27]
	s_waitcnt vmcnt(15)
; __device__ __forceinline__ float bf2f(u16 v) { return __uint_as_float(((uint32_t)v) << 16); }
; __device__ __forceinline__ uint2 pack4(float a, float b, float c, float d) { return make_uint2(pack2(a, b), pack2(c, d)); }
; __device__ __forceinline__ void store_pair16(u16* rowbase, const int fq, uint2 a, uint2 b) {
;   auto r0 = __builtin_amdgcn_permlane16_swap(a.x, b.x, false, false);
;   auto r1 = __builtin_amdgcn_permlane16_swap(a.y, b.y, false, false);
;   *(uint4*)(rowbase + (fq & 1) * 16 + (fq >> 1) * 8) = make_uint4(r0[0], r1[0], r0[1], r1[1]);
; }
; __device__ __forceinline__ void load_pair16(const u16* rowbase, const int fq, uint2& a, uint2& b) {
;   const uint4 v = *(const uint4*)(rowbase + (fq & 1) * 16 + (fq >> 1) * 8);
;   auto r0 = __builtin_amdgcn_permlane16_swap(v.x, v.z, false, false);
;   auto r1 = __builtin_amdgcn_permlane16_swap(v.y, v.w, false, false);
;   a = make_uint2(r0[0], r1[0]); b = make_uint2(r0[1], r1[1]);
; }
; __global__ void __launch_bounds__(NTHREADS, 2) fwd_megakernel(Params p_arg) {
;     ...
;         for (int np = 0; np < 2; ++np) {
;           uint2 rr[2], ov[2];
;           load_pair16(ZSBp + (eoff + (unsigned)(m * 16 * 1024 + np * 32)), fq, rr[0], rr[1]);
; #pragma unroll
;           for (int q = 0; q < 2; ++q) {
;             const int n = np * 2 + q;
;             ov[q] = pack4(acc[m][n][0] * bf2f((u16)(rr[q].x & 0xffffu)), acc[m][n][1] * bf2f((u16)(rr[q].x >> 16)),
;                           acc[m][n][2] * bf2f((u16)(rr[q].y & 0xffffu)), acc[m][n][3] * bf2f((u16)(rr[q].y >> 16)));
;           }
;           store_pair16(H + (eoff + (unsigned)(m * 16 * 1024 + np * 32)), fq, ov[0], ov[1]);
;         }
	v_mov_b32_e32 v14, v188
	v_mov_b32_e32 v15, v189
	v_mov_b32_e32 v16, v190
	v_mov_b32_e32 v17, v191
	v_mov_b32_e32 v70, v16
	v_mov_b32_e32 v71, v17
	s_nop 0
	v_permlane16_swap_b32_e32 v14, v70
	v_permlane16_swap_b32_e32 v15, v71
	v_lshlrev_b32_e32 v16, 16, v14
	v_and_b32_e32 v17, 0xffff0000, v14
	v_lshlrev_b32_e32 v14, 16, v15
	v_and_b32_e32 v15, 0xffff0000, v15
	v_pk_mul_f32 v[16:17], v[110:111], v[16:17]
	v_pk_mul_f32 v[28:29], v[112:113], v[14:15]
	v_cvt_pk_bf16_f32 v14, v16, v17
	v_cvt_pk_bf16_f32 v15, v28, v29
	v_lshlrev_b32_e32 v16, 16, v70
	v_and_b32_e32 v17, 0xffff0000, v70
	v_lshlrev_b32_e32 v28, 16, v71
	v_and_b32_e32 v29, 0xffff0000, v71
	v_pk_mul_f32 v[16:17], v[106:107], v[16:17]
	v_pk_mul_f32 v[28:29], v[108:109], v[28:29]
	v_cvt_pk_bf16_f32 v16, v16, v17
	v_cvt_pk_bf16_f32 v17, v28, v29
	s_nop 0
	v_permlane16_swap_b32_e32 v14, v16
	v_permlane16_swap_b32_e32 v15, v17
	global_store_dwordx4 v[26:27], v[14:17], off
	s_nop 1
	v_add_u32_e32 v14, 0x4020, v0
	v_mov_b32_e32 v15, v1
	v_lshlrev_b64 v[26:27], 1, v[14:15]
	v_lshl_add_u64 v[14:15], v[132:133], 0, v[26:27]
	v_lshl_add_u64 v[26:27], v[134:135], 0, v[26:27]
	s_waitcnt vmcnt(15)
	v_mov_b32_e32 v14, v196
	v_mov_b32_e32 v15, v197
	v_mov_b32_e32 v16, v198
	v_mov_b32_e32 v17, v199
	v_mov_b32_e32 v70, v16
	v_mov_b32_e32 v71, v17
	s_nop 0
	v_permlane16_swap_b32_e32 v14, v70
	v_permlane16_swap_b32_e32 v15, v71
	v_lshlrev_b32_e32 v16, 16, v14
	v_and_b32_e32 v17, 0xffff0000, v14
	v_lshlrev_b32_e32 v14, 16, v15
	v_and_b32_e32 v15, 0xffff0000, v15
	v_pk_mul_f32 v[16:17], v[102:103], v[16:17]
	v_pk_mul_f32 v[28:29], v[104:105], v[14:15]
	v_cvt_pk_bf16_f32 v14, v16, v17
	v_cvt_pk_bf16_f32 v15, v28, v29
	v_lshlrev_b32_e32 v16, 16, v70
	v_and_b32_e32 v17, 0xffff0000, v70
	v_lshlrev_b32_e32 v28, 16, v71
	v_and_b32_e32 v29, 0xffff0000, v71
	v_pk_mul_f32 v[16:17], v[98:99], v[16:17]
	v_pk_mul_f32 v[28:29], v[100:101], v[28:29]
	v_cvt_pk_bf16_f32 v16, v16, v17
	v_cvt_pk_bf16_f32 v17, v28, v29
	s_nop 0
	v_permlane16_swap_b32_e32 v14, v16
	v_permlane16_swap_b32_e32 v15, v17
	global_store_dwordx4 v[26:27], v[14:17], off
	s_nop 1
	v_add_u32_e32 v14, 0x8000, v0
	v_mov_b32_e32 v15, v1
	v_lshlrev_b64 v[26:27], 1, v[14:15]
	v_lshl_add_u64 v[14:15], v[132:133], 0, v[26:27]
	v_lshl_add_u64 v[26:27], v[134:135], 0, v[26:27]
	s_waitcnt vmcnt(15)
	v_mov_b32_e32 v14, v200
	v_mov_b32_e32 v15, v201
	v_mov_b32_e32 v16, v202
	v_mov_b32_e32 v17, v203
	v_mov_b32_e32 v70, v16
	v_mov_b32_e32 v71, v17
	s_nop 0
	v_permlane16_swap_b32_e32 v14, v70
	v_permlane16_swap_b32_e32 v15, v71
	v_lshlrev_b32_e32 v16, 16, v14
	v_and_b32_e32 v17, 0xffff0000, v14
	v_lshlrev_b32_e32 v14, 16, v15
	v_and_b32_e32 v15, 0xffff0000, v15
	v_pk_mul_f32 v[16:17], v[94:95], v[16:17]
	v_pk_mul_f32 v[28:29], v[96:97], v[14:15]
	v_cvt_pk_bf16_f32 v14, v16, v17
	v_cvt_pk_bf16_f32 v15, v28, v29
	v_lshlrev_b32_e32 v16, 16, v70
	v_and_b32_e32 v17, 0xffff0000, v70
	v_lshlrev_b32_e32 v28, 16, v71
	v_and_b32_e32 v29, 0xffff0000, v71
	v_pk_mul_f32 v[16:17], v[90:91], v[16:17]
	v_pk_mul_f32 v[28:29], v[92:93], v[28:29]
	v_cvt_pk_bf16_f32 v16, v16, v17
	v_cvt_pk_bf16_f32 v17, v28, v29
	s_nop 0
	v_permlane16_swap_b32_e32 v14, v16
	v_permlane16_swap_b32_e32 v15, v17
	global_store_dwordx4 v[26:27], v[14:17], off
	s_nop 1
	v_add_u32_e32 v14, 0x8020, v0
	v_mov_b32_e32 v15, v1
	v_lshlrev_b64 v[26:27], 1, v[14:15]
	v_lshl_add_u64 v[14:15], v[132:133], 0, v[26:27]
	v_lshl_add_u64 v[26:27], v[134:135], 0, v[26:27]
	s_waitcnt vmcnt(15)
	v_mov_b32_e32 v14, v204
	v_mov_b32_e32 v15, v205
	v_mov_b32_e32 v16, v206
	v_mov_b32_e32 v17, v207
	v_mov_b32_e32 v70, v16
	v_mov_b32_e32 v71, v17
	s_nop 0
	v_permlane16_swap_b32_e32 v14, v70
	v_permlane16_swap_b32_e32 v15, v71
	v_lshlrev_b32_e32 v16, 16, v14
	v_and_b32_e32 v17, 0xffff0000, v14
	v_lshlrev_b32_e32 v14, 16, v15
	v_and_b32_e32 v15, 0xffff0000, v15
	v_pk_mul_f32 v[16:17], v[86:87], v[16:17]
	v_pk_mul_f32 v[28:29], v[88:89], v[14:15]
	v_cvt_pk_bf16_f32 v14, v16, v17
	v_cvt_pk_bf16_f32 v15, v28, v29
	v_lshlrev_b32_e32 v16, 16, v70
	v_and_b32_e32 v17, 0xffff0000, v70
	v_lshlrev_b32_e32 v28, 16, v71
	v_and_b32_e32 v29, 0xffff0000, v71
	v_pk_mul_f32 v[16:17], v[82:83], v[16:17]
	v_pk_mul_f32 v[28:29], v[84:85], v[28:29]
	v_cvt_pk_bf16_f32 v16, v16, v17
	v_cvt_pk_bf16_f32 v17, v28, v29
	s_nop 0
	v_permlane16_swap_b32_e32 v14, v16
	v_permlane16_swap_b32_e32 v15, v17
	global_store_dwordx4 v[26:27], v[14:17], off
	s_nop 1
	v_add_u32_e32 v14, 0xc000, v0
	v_mov_b32_e32 v15, v1
	v_lshlrev_b64 v[26:27], 1, v[14:15]
	v_lshl_add_u64 v[14:15], v[132:133], 0, v[26:27]
	v_lshl_add_u64 v[26:27], v[134:135], 0, v[26:27]
	s_waitcnt vmcnt(15)
	v_mov_b32_e32 v14, v208
	v_mov_b32_e32 v15, v209
	v_mov_b32_e32 v16, v210
	v_mov_b32_e32 v17, v211
	v_mov_b32_e32 v70, v16
	v_mov_b32_e32 v71, v17
	s_nop 0
	v_permlane16_swap_b32_e32 v14, v70
	v_permlane16_swap_b32_e32 v15, v71
	v_lshlrev_b32_e32 v16, 16, v14
	v_and_b32_e32 v17, 0xffff0000, v14
	v_lshlrev_b32_e32 v14, 16, v15
	v_and_b32_e32 v15, 0xffff0000, v15
	v_pk_mul_f32 v[16:17], v[78:79], v[16:17]
	v_pk_mul_f32 v[28:29], v[80:81], v[14:15]
	v_cvt_pk_bf16_f32 v14, v16, v17
	v_cvt_pk_bf16_f32 v15, v28, v29
	v_lshlrev_b32_e32 v16, 16, v70
	v_and_b32_e32 v17, 0xffff0000, v70
	v_lshlrev_b32_e32 v28, 16, v71
	v_and_b32_e32 v29, 0xffff0000, v71
	v_pk_mul_f32 v[16:17], v[224:225], v[16:17]
	v_pk_mul_f32 v[28:29], v[226:227], v[28:29]
	v_cvt_pk_bf16_f32 v16, v16, v17
	v_cvt_pk_bf16_f32 v17, v28, v29
	s_nop 0
	v_permlane16_swap_b32_e32 v14, v16
	v_permlane16_swap_b32_e32 v15, v17
	global_store_dwordx4 v[26:27], v[14:17], off
	s_nop 1
	v_add_u32_e32 v14, 0xc020, v0
	v_mov_b32_e32 v15, v1
	v_lshlrev_b64 v[26:27], 1, v[14:15]
	v_lshl_add_u64 v[14:15], v[132:133], 0, v[26:27]
	v_lshl_add_u64 v[26:27], v[134:135], 0, v[26:27]
	s_waitcnt vmcnt(15)
; __device__ __forceinline__ float bf2f(u16 v) { return __uint_as_float(((uint32_t)v) << 16); }
; __device__ __forceinline__ uint2 pack4(float a, float b, float c, float d) { return make_uint2(pack2(a, b), pack2(c, d)); }
; __device__ __forceinline__ void store_pair16(u16* rowbase, const int fq, uint2 a, uint2 b) {
;   auto r0 = __builtin_amdgcn_permlane16_swap(a.x, b.x, false, false);
;   auto r1 = __builtin_amdgcn_permlane16_swap(a.y, b.y, false, false);
;   *(uint4*)(rowbase + (fq & 1) * 16 + (fq >> 1) * 8) = make_uint4(r0[0], r1[0], r0[1], r1[1]);
; }
; __device__ __forceinline__ void load_pair16(const u16* rowbase, const int fq, uint2& a, uint2& b) {
;   const uint4 v = *(const uint4*)(rowbase + (fq & 1) * 16 + (fq >> 1) * 8);
;   auto r0 = __builtin_amdgcn_permlane16_swap(v.x, v.z, false, false);
;   auto r1 = __builtin_amdgcn_permlane16_swap(v.y, v.w, false, false);
;   a = make_uint2(r0[0], r1[0]); b = make_uint2(r0[1], r1[1]);
; }
; __global__ void __launch_bounds__(NTHREADS, 2) fwd_megakernel(Params p_arg) {
;     ...
;         for (int np = 0; np < 2; ++np) {
;           uint2 rr[2], ov[2];
;           load_pair16(ZSBp + (eoff + (unsigned)(m * 16 * 1024 + np * 32)), fq, rr[0], rr[1]);
; #pragma unroll
;           for (int q = 0; q < 2; ++q) {
;             const int n = np * 2 + q;
;             ov[q] = pack4(acc[m][n][0] * bf2f((u16)(rr[q].x & 0xffffu)), acc[m][n][1] * bf2f((u16)(rr[q].x >> 16)),
;                           acc[m][n][2] * bf2f((u16)(rr[q].y & 0xffffu)), acc[m][n][3] * bf2f((u16)(rr[q].y >> 16)));
;           }
;           store_pair16(H + (eoff + (unsigned)(m * 16 * 1024 + np * 32)), fq, ov[0], ov[1]);
;         }
	v_mov_b32_e32 v14, v212
	v_mov_b32_e32 v15, v213
	v_mov_b32_e32 v16, v214
	v_mov_b32_e32 v17, v215
	v_mov_b32_e32 v70, v16
	v_mov_b32_e32 v71, v17
	s_nop 0
	v_permlane16_swap_b32_e32 v14, v70
	v_permlane16_swap_b32_e32 v15, v71
	v_lshlrev_b32_e32 v16, 16, v14
	v_and_b32_e32 v17, 0xffff0000, v14
	v_lshlrev_b32_e32 v14, 16, v15
	v_and_b32_e32 v15, 0xffff0000, v15
	v_pk_mul_f32 v[16:17], v[192:193], v[16:17]
	v_pk_mul_f32 v[28:29], v[194:195], v[14:15]
	v_cvt_pk_bf16_f32 v14, v16, v17
	v_cvt_pk_bf16_f32 v15, v28, v29
	v_lshlrev_b32_e32 v16, 16, v70
	v_and_b32_e32 v17, 0xffff0000, v70
	v_lshlrev_b32_e32 v28, 16, v71
	v_and_b32_e32 v29, 0xffff0000, v71
	v_pk_mul_f32 v[16:17], v[66:67], v[16:17]
	v_pk_mul_f32 v[28:29], v[68:69], v[28:29]
	v_cvt_pk_bf16_f32 v16, v16, v17
	v_cvt_pk_bf16_f32 v17, v28, v29
	s_nop 0
	v_permlane16_swap_b32_e32 v14, v16
	v_permlane16_swap_b32_e32 v15, v17
	global_store_dwordx4 v[26:27], v[14:17], off
	s_nop 1
	v_add_u32_e32 v14, 0x10000, v0
	v_mov_b32_e32 v15, v1
	v_lshlrev_b64 v[26:27], 1, v[14:15]
	v_lshl_add_u64 v[14:15], v[132:133], 0, v[26:27]
	v_lshl_add_u64 v[26:27], v[134:135], 0, v[26:27]
	s_add_i32 s36, s36, 1
	s_mov_b64 s[0:1], 0
	s_mov_b64 s[98:99], s[54:55]
	s_waitcnt vmcnt(15)
	v_mov_b32_e32 v14, v216
	v_mov_b32_e32 v15, v217
	v_mov_b32_e32 v16, v218
	v_mov_b32_e32 v17, v219
	v_mov_b32_e32 v66, v16
	v_mov_b32_e32 v67, v17
	s_nop 0
	v_permlane16_swap_b32_e32 v14, v66
	v_permlane16_swap_b32_e32 v15, v67
	v_lshlrev_b32_e32 v16, 16, v14
	v_and_b32_e32 v17, 0xffff0000, v14
	v_lshlrev_b32_e32 v14, 16, v15
	v_and_b32_e32 v15, 0xffff0000, v15
	v_pk_mul_f32 v[16:17], v[62:63], v[16:17]
	v_pk_mul_f32 v[28:29], v[64:65], v[14:15]
	v_cvt_pk_bf16_f32 v14, v16, v17
	v_cvt_pk_bf16_f32 v15, v28, v29
	v_lshlrev_b32_e32 v16, 16, v66
	v_and_b32_e32 v17, 0xffff0000, v66
	v_lshlrev_b32_e32 v28, 16, v67
	v_and_b32_e32 v29, 0xffff0000, v67
	v_pk_mul_f32 v[16:17], v[58:59], v[16:17]
	v_pk_mul_f32 v[28:29], v[60:61], v[28:29]
	v_cvt_pk_bf16_f32 v16, v16, v17
	v_cvt_pk_bf16_f32 v17, v28, v29
	s_nop 0
	v_permlane16_swap_b32_e32 v14, v16
	v_permlane16_swap_b32_e32 v15, v17
	global_store_dwordx4 v[26:27], v[14:17], off
	s_nop 1
	v_add_u32_e32 v14, 0x10020, v0
	v_mov_b32_e32 v15, v1
	v_lshlrev_b64 v[26:27], 1, v[14:15]
	v_lshl_add_u64 v[14:15], v[132:133], 0, v[26:27]
	v_lshl_add_u64 v[26:27], v[134:135], 0, v[26:27]
	s_waitcnt vmcnt(15)
	v_mov_b32_e32 v14, v220
	v_mov_b32_e32 v15, v221
	v_mov_b32_e32 v16, v222
	v_mov_b32_e32 v17, v223
	v_mov_b32_e32 v58, v16
	v_mov_b32_e32 v59, v17
	s_nop 0
	v_permlane16_swap_b32_e32 v14, v58
	v_permlane16_swap_b32_e32 v15, v59
	v_lshlrev_b32_e32 v16, 16, v14
	v_and_b32_e32 v17, 0xffff0000, v14
	v_lshlrev_b32_e32 v14, 16, v15
	v_and_b32_e32 v15, 0xffff0000, v15
	v_pk_mul_f32 v[16:17], v[54:55], v[16:17]
	v_pk_mul_f32 v[28:29], v[56:57], v[14:15]
	v_cvt_pk_bf16_f32 v14, v16, v17
	v_cvt_pk_bf16_f32 v15, v28, v29
	v_lshlrev_b32_e32 v16, 16, v58
	v_and_b32_e32 v17, 0xffff0000, v58
	v_lshlrev_b32_e32 v28, 16, v59
	v_and_b32_e32 v29, 0xffff0000, v59
	v_pk_mul_f32 v[16:17], v[50:51], v[16:17]
	v_pk_mul_f32 v[28:29], v[52:53], v[28:29]
	v_cvt_pk_bf16_f32 v16, v16, v17
	v_cvt_pk_bf16_f32 v17, v28, v29
	s_nop 0
	v_permlane16_swap_b32_e32 v14, v16
	v_permlane16_swap_b32_e32 v15, v17
	global_store_dwordx4 v[26:27], v[14:17], off
	s_nop 1
	v_add_u32_e32 v14, 0x14000, v0
	v_mov_b32_e32 v15, v1
	v_lshlrev_b64 v[26:27], 1, v[14:15]
	v_lshl_add_u64 v[14:15], v[132:133], 0, v[26:27]
	v_lshl_add_u64 v[26:27], v[134:135], 0, v[26:27]
	s_waitcnt vmcnt(15)
	v_mov_b32_e32 v14, v228
	v_mov_b32_e32 v15, v229
	v_mov_b32_e32 v16, v230
	v_mov_b32_e32 v17, v231
	v_mov_b32_e32 v50, v16
	v_mov_b32_e32 v51, v17
	s_nop 0
	v_permlane16_swap_b32_e32 v14, v50
	v_permlane16_swap_b32_e32 v15, v51
	v_lshlrev_b32_e32 v16, 16, v14
	v_and_b32_e32 v17, 0xffff0000, v14
	v_lshlrev_b32_e32 v14, 16, v15
	v_and_b32_e32 v15, 0xffff0000, v15
	v_pk_mul_f32 v[16:17], v[46:47], v[16:17]
	v_pk_mul_f32 v[28:29], v[48:49], v[14:15]
	v_cvt_pk_bf16_f32 v14, v16, v17
	v_cvt_pk_bf16_f32 v15, v28, v29
	v_lshlrev_b32_e32 v16, 16, v50
	v_and_b32_e32 v17, 0xffff0000, v50
	v_lshlrev_b32_e32 v28, 16, v51
	v_and_b32_e32 v29, 0xffff0000, v51
	v_pk_mul_f32 v[16:17], v[42:43], v[16:17]
	v_pk_mul_f32 v[28:29], v[44:45], v[28:29]
	v_cvt_pk_bf16_f32 v16, v16, v17
	v_cvt_pk_bf16_f32 v17, v28, v29
	s_nop 0
	v_permlane16_swap_b32_e32 v14, v16
	v_permlane16_swap_b32_e32 v15, v17
	global_store_dwordx4 v[26:27], v[14:17], off
	s_nop 1
	v_add_u32_e32 v14, 0x14020, v0
	v_mov_b32_e32 v15, v1
	v_lshlrev_b64 v[26:27], 1, v[14:15]
	v_lshl_add_u64 v[14:15], v[132:133], 0, v[26:27]
	v_lshl_add_u64 v[26:27], v[134:135], 0, v[26:27]
	s_waitcnt vmcnt(15)
; __device__ __forceinline__ float bf2f(u16 v) { return __uint_as_float(((uint32_t)v) << 16); }
; __device__ __forceinline__ uint2 pack4(float a, float b, float c, float d) { return make_uint2(pack2(a, b), pack2(c, d)); }
; __device__ __forceinline__ void store_pair16(u16* rowbase, const int fq, uint2 a, uint2 b) {
;   auto r0 = __builtin_amdgcn_permlane16_swap(a.x, b.x, false, false);
;   auto r1 = __builtin_amdgcn_permlane16_swap(a.y, b.y, false, false);
;   *(uint4*)(rowbase + (fq & 1) * 16 + (fq >> 1) * 8) = make_uint4(r0[0], r1[0], r0[1], r1[1]);
; }
; __device__ __forceinline__ void load_pair16(const u16* rowbase, const int fq, uint2& a, uint2& b) {
;   const uint4 v = *(const uint4*)(rowbase + (fq & 1) * 16 + (fq >> 1) * 8);
;   auto r0 = __builtin_amdgcn_permlane16_swap(v.x, v.z, false, false);
;   auto r1 = __builtin_amdgcn_permlane16_swap(v.y, v.w, false, false);
;   a = make_uint2(r0[0], r1[0]); b = make_uint2(r0[1], r1[1]);
; }
; __global__ void __launch_bounds__(NTHREADS, 2) fwd_megakernel(Params p_arg) {
;     ...
;         for (int np = 0; np < 2; ++np) {
;           uint2 rr[2], ov[2];
;           load_pair16(ZSBp + (eoff + (unsigned)(m * 16 * 1024 + np * 32)), fq, rr[0], rr[1]);
; #pragma unroll
;           for (int q = 0; q < 2; ++q) {
;             const int n = np * 2 + q;
;             ov[q] = pack4(acc[m][n][0] * bf2f((u16)(rr[q].x & 0xffffu)), acc[m][n][1] * bf2f((u16)(rr[q].x >> 16)),
;                           acc[m][n][2] * bf2f((u16)(rr[q].y & 0xffffu)), acc[m][n][3] * bf2f((u16)(rr[q].y >> 16)));
;           }
;           store_pair16(H + (eoff + (unsigned)(m * 16 * 1024 + np * 32)), fq, ov[0], ov[1]);
;         }
	v_mov_b32_e32 v14, v232
	v_mov_b32_e32 v15, v233
	v_mov_b32_e32 v16, v234
	v_mov_b32_e32 v17, v235
	v_mov_b32_e32 v42, v16
	v_mov_b32_e32 v43, v17
	s_nop 0
	v_permlane16_swap_b32_e32 v14, v42
	v_permlane16_swap_b32_e32 v15, v43
	v_lshlrev_b32_e32 v16, 16, v14
	v_and_b32_e32 v17, 0xffff0000, v14
	v_lshlrev_b32_e32 v14, 16, v15
	v_and_b32_e32 v15, 0xffff0000, v15
	v_pk_mul_f32 v[16:17], v[38:39], v[16:17]
	v_pk_mul_f32 v[28:29], v[40:41], v[14:15]
	v_cvt_pk_bf16_f32 v14, v16, v17
	v_cvt_pk_bf16_f32 v15, v28, v29
	v_lshlrev_b32_e32 v16, 16, v42
	v_and_b32_e32 v17, 0xffff0000, v42
	v_lshlrev_b32_e32 v28, 16, v43
	v_and_b32_e32 v29, 0xffff0000, v43
	v_pk_mul_f32 v[16:17], v[34:35], v[16:17]
	v_pk_mul_f32 v[28:29], v[36:37], v[28:29]
	v_cvt_pk_bf16_f32 v16, v16, v17
	v_cvt_pk_bf16_f32 v17, v28, v29
	s_nop 0
	v_permlane16_swap_b32_e32 v14, v16
	v_permlane16_swap_b32_e32 v15, v17
	global_store_dwordx4 v[26:27], v[14:17], off
	s_nop 1
	v_add_u32_e32 v14, 0x18000, v0
	v_mov_b32_e32 v15, v1
	v_lshlrev_b64 v[26:27], 1, v[14:15]
	v_lshl_add_u64 v[14:15], v[132:133], 0, v[26:27]
	v_lshl_add_u64 v[26:27], v[134:135], 0, v[26:27]
	s_waitcnt vmcnt(15)
	v_mov_b32_e32 v14, v236
	v_mov_b32_e32 v15, v237
	v_mov_b32_e32 v16, v238
	v_mov_b32_e32 v17, v239
	v_mov_b32_e32 v34, v16
	v_mov_b32_e32 v35, v17
	s_nop 0
	v_permlane16_swap_b32_e32 v14, v34
	v_permlane16_swap_b32_e32 v15, v35
	v_lshlrev_b32_e32 v16, 16, v14
	v_and_b32_e32 v17, 0xffff0000, v14
	v_lshlrev_b32_e32 v14, 16, v15
	v_and_b32_e32 v15, 0xffff0000, v15
	v_pk_mul_f32 v[16:17], v[30:31], v[16:17]
	v_pk_mul_f32 v[28:29], v[32:33], v[14:15]
	v_cvt_pk_bf16_f32 v14, v16, v17
	v_cvt_pk_bf16_f32 v15, v28, v29
	v_lshlrev_b32_e32 v16, 16, v34
	v_and_b32_e32 v17, 0xffff0000, v34
	v_lshlrev_b32_e32 v28, 16, v35
	v_and_b32_e32 v29, 0xffff0000, v35
	v_pk_mul_f32 v[16:17], v[150:151], v[16:17]
	v_pk_mul_f32 v[28:29], v[152:153], v[28:29]
	v_cvt_pk_bf16_f32 v16, v16, v17
	v_cvt_pk_bf16_f32 v17, v28, v29
	s_nop 0
	v_permlane16_swap_b32_e32 v14, v16
	v_permlane16_swap_b32_e32 v15, v17
	global_store_dwordx4 v[26:27], v[14:17], off
	s_nop 1
	v_add_u32_e32 v14, 0x18020, v0
	v_mov_b32_e32 v15, v1
	v_lshlrev_b64 v[26:27], 1, v[14:15]
	v_lshl_add_u64 v[14:15], v[132:133], 0, v[26:27]
	s_waitcnt vmcnt(15)
	v_mov_b32_e32 v14, v240
	v_mov_b32_e32 v15, v241
	v_mov_b32_e32 v16, v242
	v_mov_b32_e32 v17, v243
	v_mov_b32_e32 v28, v16
	s_nop 1
	v_permlane16_swap_b32_e32 v14, v28
	v_mov_b32_e32 v29, v17
	s_nop 1
	v_permlane16_swap_b32_e32 v15, v29
	v_lshlrev_b32_e32 v16, 16, v14
	v_and_b32_e32 v17, 0xffff0000, v14
	v_pk_mul_f32 v[16:17], v[22:23], v[16:17]
	v_lshlrev_b32_e32 v14, 16, v15
	v_and_b32_e32 v15, 0xffff0000, v15
	v_pk_mul_f32 v[22:23], v[24:25], v[14:15]
	v_cvt_pk_bf16_f32 v14, v16, v17
	v_lshlrev_b32_e32 v16, 16, v28
	v_and_b32_e32 v17, 0xffff0000, v28
	v_pk_mul_f32 v[16:17], v[18:19], v[16:17]
	v_lshlrev_b32_e32 v18, 16, v29
	v_and_b32_e32 v19, 0xffff0000, v29
	v_pk_mul_f32 v[18:19], v[20:21], v[18:19]
	v_cvt_pk_bf16_f32 v15, v22, v23
	v_cvt_pk_bf16_f32 v16, v16, v17
	v_cvt_pk_bf16_f32 v17, v18, v19
	s_nop 0
	v_permlane16_swap_b32_e32 v14, v16
	v_permlane16_swap_b32_e32 v15, v17
	v_lshl_add_u64 v[18:19], v[134:135], 0, v[26:27]
	global_store_dwordx4 v[18:19], v[14:17], off
	s_nop 1
	v_add_u32_e32 v14, 0x1c000, v0
	v_mov_b32_e32 v15, v1
	v_lshlrev_b64 v[18:19], 1, v[14:15]
	v_lshl_add_u64 v[14:15], v[132:133], 0, v[18:19]
	v_add_u32_e32 v0, 0x1c020, v0
	s_waitcnt vmcnt(15)
	v_mov_b32_e32 v14, v244
	v_mov_b32_e32 v15, v245
	v_mov_b32_e32 v16, v246
	v_mov_b32_e32 v17, v247
	v_mov_b32_e32 v22, v16
	s_nop 1
	v_permlane16_swap_b32_e32 v14, v22
	v_mov_b32_e32 v23, v17
	s_nop 1
	v_permlane16_swap_b32_e32 v15, v23
	v_lshlrev_b32_e32 v16, 16, v14
	v_and_b32_e32 v17, 0xffff0000, v14
	v_pk_mul_f32 v[16:17], v[140:141], v[16:17]
	v_lshlrev_b32_e32 v14, 16, v15
	v_and_b32_e32 v15, 0xffff0000, v15
	v_pk_mul_f32 v[20:21], v[142:143], v[14:15]
	v_cvt_pk_bf16_f32 v14, v16, v17
	v_lshlrev_b32_e32 v16, 16, v22
	v_and_b32_e32 v17, 0xffff0000, v22
	v_pk_mul_f32 v[10:11], v[10:11], v[16:17]
	v_lshlrev_b32_e32 v16, 16, v23
	v_and_b32_e32 v17, 0xffff0000, v23
	v_pk_mul_f32 v[12:13], v[12:13], v[16:17]
	v_cvt_pk_bf16_f32 v15, v20, v21
	v_cvt_pk_bf16_f32 v16, v10, v11
	v_cvt_pk_bf16_f32 v17, v12, v13
	s_nop 0
	v_permlane16_swap_b32_e32 v14, v16
	v_permlane16_swap_b32_e32 v15, v17
	v_lshl_add_u64 v[10:11], v[134:135], 0, v[18:19]
	global_store_dwordx4 v[10:11], v[14:17], off
	s_nop 1
	v_lshlrev_b64 v[14:15], 1, v[0:1]
	v_lshl_add_u64 v[10:11], v[132:133], 0, v[14:15]
	s_waitcnt vmcnt(15)
	v_mov_b32_e32 v10, v248
	v_mov_b32_e32 v11, v249
	v_mov_b32_e32 v12, v250
	v_mov_b32_e32 v13, v251
	v_mov_b32_e32 v0, v12
	v_mov_b32_e32 v16, v13
	s_nop 0
	v_permlane16_swap_b32_e32 v10, v0
	v_permlane16_swap_b32_e32 v11, v16
	v_lshlrev_b32_e32 v12, 16, v10
	v_and_b32_e32 v13, 0xffff0000, v10
	v_lshlrev_b32_e32 v10, 16, v11
	v_and_b32_e32 v11, 0xffff0000, v11
	v_pk_mul_f32 v[6:7], v[6:7], v[12:13]
	v_pk_mul_f32 v[8:9], v[8:9], v[10:11]
	v_cvt_pk_bf16_f32 v6, v6, v7
	v_cvt_pk_bf16_f32 v7, v8, v9
	v_lshlrev_b32_e32 v8, 16, v0
	v_and_b32_e32 v9, 0xffff0000, v0
	v_pk_mul_f32 v[2:3], v[2:3], v[8:9]
	v_lshlrev_b32_e32 v8, 16, v16
	v_and_b32_e32 v9, 0xffff0000, v16
	v_pk_mul_f32 v[4:5], v[4:5], v[8:9]
	v_cvt_pk_bf16_f32 v8, v2, v3
	v_cvt_pk_bf16_f32 v9, v4, v5
	s_nop 0
	v_permlane16_swap_b32_e32 v6, v8
	v_permlane16_swap_b32_e32 v7, v9
	v_lshl_add_u64 v[2:3], v[134:135], 0, v[14:15]
	global_store_dwordx4 v[2:3], v[6:9], off
